# GEMM2 residual epilogue (f32 x path) rewritten with batched rs2/x loads and a 1-row-ahead load pipeline; mid-K RMS rescale loads batched (one wait instead of eight), on top of conversion-loop counted
# speedup vs baseline: 1.0296x; 1.0170x over previous
; __device__ __forceinline__ float fx_get(const long long* p, float inv) { return (float)(*(const GAS long long*)p) * inv; }
;     __device__ __forceinline__ void mid(f32x4 (&acc)[2][2][4][2], const pg8::Unit& u, int wr, int fr) const {
;         const int row0 = u.pm * 256 + wr * 64 + fr;
; #pragma unroll
;         for (int ai = 0; ai < 2; ++ai)
; #pragma unroll
;             for (int m = 0; m < 4; ++m) { int r = row0 + ai * 128 + m * 16; asm volatile("" : "+v"(r));
;                 const float a = fx_get(rs2 + r, FX_RS_INV) * (1.0f / 1024.0f) + RMS_EPS, b = fx_get(rs2 + SEQ + r, FX_RS_INV) * (1.0f / 1024.0f) + RMS_EPS;
;                 const float ratio = __builtin_amdgcn_sqrtf(b * __builtin_amdgcn_rcpf(a));
; #pragma unroll
;                 for (int bj = 0; bj < 2; ++bj)
; #pragma unroll
;                     for (int n = 0; n < 2; ++n) acc[ai][bj][m][n] *= ratio; }
.LBB0_421:
	s_cmp_eq_u32 s62, s34
	s_cselect_b64 s[36:37], -1, 0
	s_and_b64 s[36:37], s[24:25], s[36:37]
	s_andn2_b64 vcc, exec, s[36:37]
	s_cbranch_vccnz .LBB0_423
	v_mov_b32_e32 v0, v184
	v_ashrrev_i32_e32 v1, 31, v0
	v_lshlrev_b64 v[0:1], 3, v[0:1]
	v_lshl_add_u64 v[136:137], s[16:17], 0, v[0:1]
	global_load_dwordx2 v[136:137], v[136:137], off
	v_lshl_add_u64 v[186:187], s[26:27], 0, v[0:1]
	global_load_dwordx2 v[186:187], v[186:187], off
	v_mov_b32_e32 v0, v182
	v_ashrrev_i32_e32 v1, 31, v0
	v_lshlrev_b64 v[0:1], 3, v[0:1]
	v_lshl_add_u64 v[138:139], s[16:17], 0, v[0:1]
	global_load_dwordx2 v[138:139], v[138:139], off
	v_lshl_add_u64 v[188:189], s[26:27], 0, v[0:1]
	global_load_dwordx2 v[188:189], v[188:189], off
	v_mov_b32_e32 v0, v180
	v_ashrrev_i32_e32 v1, 31, v0
	v_lshlrev_b64 v[0:1], 3, v[0:1]
	v_lshl_add_u64 v[140:141], s[16:17], 0, v[0:1]
	global_load_dwordx2 v[140:141], v[140:141], off
	v_lshl_add_u64 v[190:191], s[26:27], 0, v[0:1]
	global_load_dwordx2 v[190:191], v[190:191], off
	v_mov_b32_e32 v0, v178
	v_ashrrev_i32_e32 v1, 31, v0
	v_lshlrev_b64 v[0:1], 3, v[0:1]
	v_lshl_add_u64 v[142:143], s[16:17], 0, v[0:1]
	global_load_dwordx2 v[142:143], v[142:143], off
	v_lshl_add_u64 v[192:193], s[26:27], 0, v[0:1]
	global_load_dwordx2 v[192:193], v[192:193], off
	v_mov_b32_e32 v0, v176
	v_ashrrev_i32_e32 v1, 31, v0
	v_lshlrev_b64 v[0:1], 3, v[0:1]
	v_lshl_add_u64 v[144:145], s[16:17], 0, v[0:1]
	global_load_dwordx2 v[144:145], v[144:145], off
	v_lshl_add_u64 v[194:195], s[26:27], 0, v[0:1]
	global_load_dwordx2 v[194:195], v[194:195], off
	v_mov_b32_e32 v0, v174
	v_ashrrev_i32_e32 v1, 31, v0
	v_lshlrev_b64 v[0:1], 3, v[0:1]
	v_lshl_add_u64 v[146:147], s[16:17], 0, v[0:1]
	global_load_dwordx2 v[146:147], v[146:147], off
	v_lshl_add_u64 v[196:197], s[26:27], 0, v[0:1]
	global_load_dwordx2 v[196:197], v[196:197], off
	v_mov_b32_e32 v0, v172
	v_ashrrev_i32_e32 v1, 31, v0
	v_lshlrev_b64 v[0:1], 3, v[0:1]
	v_lshl_add_u64 v[148:149], s[16:17], 0, v[0:1]
	global_load_dwordx2 v[148:149], v[148:149], off
	v_lshl_add_u64 v[198:199], s[26:27], 0, v[0:1]
	global_load_dwordx2 v[198:199], v[198:199], off
	v_mov_b32_e32 v0, v170
	v_ashrrev_i32_e32 v1, 31, v0
	v_lshlrev_b64 v[0:1], 3, v[0:1]
	v_lshl_add_u64 v[150:151], s[16:17], 0, v[0:1]
	global_load_dwordx2 v[150:151], v[150:151], off
	v_lshl_add_u64 v[200:201], s[26:27], 0, v[0:1]
	global_load_dwordx2 v[200:201], v[200:201], off
	s_waitcnt vmcnt(0)
	v_xor_b32_e32 v3, v136, v137
	v_ashrrev_i32_e32 v3, 31, v3
	v_ffbh_i32_e32 v152, v137
	v_add_u32_e32 v3, 32, v3
	v_add_u32_e32 v152, -1, v152
	v_min_u32_e32 v3, v152, v3
	v_lshlrev_b64 v[136:137], v3, v[136:137]
	v_min_u32_e32 v136, 1, v136
	v_or_b32_e32 v136, v137, v136
	v_cvt_f32_i32_e32 v136, v136
	v_sub_u32_e32 v3, 32, v3
	v_ffbh_i32_e32 v137, v187
	v_add_u32_e32 v137, -1, v137
	v_ldexp_f32 v3, v136, v3
	v_xor_b32_e32 v136, v186, v187
	v_ashrrev_i32_e32 v136, 31, v136
	v_add_u32_e32 v136, 32, v136
	v_min_u32_e32 v136, v137, v136
	v_lshlrev_b64 v[186:187], v136, v[186:187]
	v_min_u32_e32 v186, 1, v186
	v_or_b32_e32 v186, v187, v186
	v_cvt_f32_i32_e32 v186, v186
	v_mul_f32_e32 v3, 0x33800000, v3
	v_fmamk_f32 v3, v3, 0x3a800000, v223
	v_sub_u32_e32 v187, 32, v136
	v_ldexp_f32 v186, v186, v187
	v_rcp_f32_e32 v187, v3
	v_mul_f32_e32 v186, 0x33800000, v186
	v_fmamk_f32 v186, v186, 0x3a800000, v223
	v_mul_f32_e32 v186, v186, v187
	v_sqrt_f32_e32 v186, v186
	s_nop 0
	v_pk_mul_f32 v[130:131], v[130:131], v[186:187] op_sel_hi:[1,0]
	v_pk_mul_f32 v[128:129], v[128:129], v[186:187] op_sel_hi:[1,0]
	v_pk_mul_f32 v[126:127], v[126:127], v[186:187] op_sel_hi:[1,0]
	v_pk_mul_f32 v[124:125], v[124:125], v[186:187] op_sel_hi:[1,0]
	v_pk_mul_f32 v[122:123], v[122:123], v[186:187] op_sel_hi:[1,0]
	v_pk_mul_f32 v[120:121], v[120:121], v[186:187] op_sel_hi:[1,0]
	v_pk_mul_f32 v[118:119], v[118:119], v[186:187] op_sel_hi:[1,0]
	v_pk_mul_f32 v[116:117], v[116:117], v[186:187] op_sel_hi:[1,0]
	v_xor_b32_e32 v153, v138, v139
	v_ashrrev_i32_e32 v153, 31, v153
	v_ffbh_i32_e32 v202, v139
	v_add_u32_e32 v153, 32, v153
	v_add_u32_e32 v202, -1, v202
	v_min_u32_e32 v153, v202, v153
	v_lshlrev_b64 v[138:139], v153, v[138:139]
	v_min_u32_e32 v138, 1, v138
	v_or_b32_e32 v138, v139, v138
	v_cvt_f32_i32_e32 v138, v138
	v_sub_u32_e32 v153, 32, v153
	v_ffbh_i32_e32 v139, v189
	v_add_u32_e32 v139, -1, v139
	v_ldexp_f32 v153, v138, v153
	v_xor_b32_e32 v138, v188, v189
	v_ashrrev_i32_e32 v138, 31, v138
	v_add_u32_e32 v138, 32, v138
	v_min_u32_e32 v138, v139, v138
	v_lshlrev_b64 v[188:189], v138, v[188:189]
	v_min_u32_e32 v188, 1, v188
	v_or_b32_e32 v188, v189, v188
	v_cvt_f32_i32_e32 v188, v188
	v_mul_f32_e32 v153, 0x33800000, v153
	v_fmamk_f32 v153, v153, 0x3a800000, v223
	v_sub_u32_e32 v189, 32, v138
	v_ldexp_f32 v188, v188, v189
	v_rcp_f32_e32 v189, v153
	v_mul_f32_e32 v188, 0x33800000, v188
	v_fmamk_f32 v188, v188, 0x3a800000, v223
	v_mul_f32_e32 v188, v188, v189
	v_sqrt_f32_e32 v188, v188
	s_nop 0
	v_pk_mul_f32 v[114:115], v[114:115], v[188:189] op_sel_hi:[1,0]
	v_pk_mul_f32 v[112:113], v[112:113], v[188:189] op_sel_hi:[1,0]
	v_pk_mul_f32 v[110:111], v[110:111], v[188:189] op_sel_hi:[1,0]
	v_pk_mul_f32 v[108:109], v[108:109], v[188:189] op_sel_hi:[1,0]
	v_pk_mul_f32 v[106:107], v[106:107], v[188:189] op_sel_hi:[1,0]
	v_pk_mul_f32 v[104:105], v[104:105], v[188:189] op_sel_hi:[1,0]
	v_pk_mul_f32 v[102:103], v[102:103], v[188:189] op_sel_hi:[1,0]
	v_pk_mul_f32 v[100:101], v[100:101], v[188:189] op_sel_hi:[1,0]
	v_xor_b32_e32 v3, v140, v141
	v_ashrrev_i32_e32 v3, 31, v3
	v_ffbh_i32_e32 v152, v141
	v_add_u32_e32 v3, 32, v3
	v_add_u32_e32 v152, -1, v152
	v_min_u32_e32 v3, v152, v3
; __device__ __forceinline__ float fx_get(const long long* p, float inv) { return (float)(*(const GAS long long*)p) * inv; }
;     __device__ __forceinline__ void mid(f32x4 (&acc)[2][2][4][2], const pg8::Unit& u, int wr, int fr) const {
;         const int row0 = u.pm * 256 + wr * 64 + fr;
; #pragma unroll
;         for (int ai = 0; ai < 2; ++ai)
; #pragma unroll
;             for (int m = 0; m < 4; ++m) { int r = row0 + ai * 128 + m * 16; asm volatile("" : "+v"(r));
;                 const float a = fx_get(rs2 + r, FX_RS_INV) * (1.0f / 1024.0f) + RMS_EPS, b = fx_get(rs2 + SEQ + r, FX_RS_INV) * (1.0f / 1024.0f) + RMS_EPS;
;                 const float ratio = __builtin_amdgcn_sqrtf(b * __builtin_amdgcn_rcpf(a));
; #pragma unroll
;                 for (int bj = 0; bj < 2; ++bj)
; #pragma unroll
;                     for (int n = 0; n < 2; ++n) acc[ai][bj][m][n] *= ratio; }
	v_lshlrev_b64 v[140:141], v3, v[140:141]
	v_min_u32_e32 v140, 1, v140
	v_or_b32_e32 v140, v141, v140
	v_cvt_f32_i32_e32 v140, v140
	v_sub_u32_e32 v3, 32, v3
	v_ffbh_i32_e32 v141, v191
	v_add_u32_e32 v141, -1, v141
	v_ldexp_f32 v3, v140, v3
	v_xor_b32_e32 v140, v190, v191
	v_ashrrev_i32_e32 v140, 31, v140
	v_add_u32_e32 v140, 32, v140
	v_min_u32_e32 v140, v141, v140
	v_lshlrev_b64 v[190:191], v140, v[190:191]
	v_min_u32_e32 v190, 1, v190
	v_or_b32_e32 v190, v191, v190
	v_cvt_f32_i32_e32 v190, v190
	v_mul_f32_e32 v3, 0x33800000, v3
	v_fmamk_f32 v3, v3, 0x3a800000, v223
	v_sub_u32_e32 v191, 32, v140
	v_ldexp_f32 v190, v190, v191
	v_rcp_f32_e32 v191, v3
	v_mul_f32_e32 v190, 0x33800000, v190
	v_fmamk_f32 v190, v190, 0x3a800000, v223
	v_mul_f32_e32 v190, v190, v191
	v_sqrt_f32_e32 v190, v190
	s_nop 0
	v_pk_mul_f32 v[98:99], v[98:99], v[190:191] op_sel_hi:[1,0]
	v_pk_mul_f32 v[96:97], v[96:97], v[190:191] op_sel_hi:[1,0]
	v_pk_mul_f32 v[94:95], v[94:95], v[190:191] op_sel_hi:[1,0]
	v_pk_mul_f32 v[92:93], v[92:93], v[190:191] op_sel_hi:[1,0]
	v_pk_mul_f32 v[90:91], v[90:91], v[190:191] op_sel_hi:[1,0]
	v_pk_mul_f32 v[88:89], v[88:89], v[190:191] op_sel_hi:[1,0]
	v_pk_mul_f32 v[86:87], v[86:87], v[190:191] op_sel_hi:[1,0]
	v_pk_mul_f32 v[84:85], v[84:85], v[190:191] op_sel_hi:[1,0]
	v_xor_b32_e32 v153, v142, v143
	v_ashrrev_i32_e32 v153, 31, v153
	v_ffbh_i32_e32 v202, v143
	v_add_u32_e32 v153, 32, v153
	v_add_u32_e32 v202, -1, v202
	v_min_u32_e32 v153, v202, v153
	v_lshlrev_b64 v[142:143], v153, v[142:143]
	v_min_u32_e32 v142, 1, v142
	v_or_b32_e32 v142, v143, v142
	v_cvt_f32_i32_e32 v142, v142
	v_sub_u32_e32 v153, 32, v153
	v_ffbh_i32_e32 v143, v193
	v_add_u32_e32 v143, -1, v143
	v_ldexp_f32 v153, v142, v153
	v_xor_b32_e32 v142, v192, v193
	v_ashrrev_i32_e32 v142, 31, v142
	v_add_u32_e32 v142, 32, v142
	v_min_u32_e32 v142, v143, v142
	v_lshlrev_b64 v[192:193], v142, v[192:193]
	v_min_u32_e32 v192, 1, v192
	v_or_b32_e32 v192, v193, v192
	v_cvt_f32_i32_e32 v192, v192
	v_mul_f32_e32 v153, 0x33800000, v153
	v_fmamk_f32 v153, v153, 0x3a800000, v223
	v_sub_u32_e32 v193, 32, v142
	v_ldexp_f32 v192, v192, v193
	v_rcp_f32_e32 v193, v153
	v_mul_f32_e32 v192, 0x33800000, v192
	v_fmamk_f32 v192, v192, 0x3a800000, v223
	v_mul_f32_e32 v192, v192, v193
	v_sqrt_f32_e32 v192, v192
	s_nop 0
	v_pk_mul_f32 v[82:83], v[82:83], v[192:193] op_sel_hi:[1,0]
	v_pk_mul_f32 v[80:81], v[80:81], v[192:193] op_sel_hi:[1,0]
	v_pk_mul_f32 v[78:79], v[78:79], v[192:193] op_sel_hi:[1,0]
	v_pk_mul_f32 v[76:77], v[76:77], v[192:193] op_sel_hi:[1,0]
	v_pk_mul_f32 v[74:75], v[74:75], v[192:193] op_sel_hi:[1,0]
	v_pk_mul_f32 v[72:73], v[72:73], v[192:193] op_sel_hi:[1,0]
	v_pk_mul_f32 v[70:71], v[70:71], v[192:193] op_sel_hi:[1,0]
	v_pk_mul_f32 v[68:69], v[68:69], v[192:193] op_sel_hi:[1,0]
	v_xor_b32_e32 v3, v144, v145
	v_ashrrev_i32_e32 v3, 31, v3
	v_ffbh_i32_e32 v152, v145
	v_add_u32_e32 v3, 32, v3
	v_add_u32_e32 v152, -1, v152
	v_min_u32_e32 v3, v152, v3
	v_lshlrev_b64 v[144:145], v3, v[144:145]
	v_min_u32_e32 v144, 1, v144
	v_or_b32_e32 v144, v145, v144
	v_cvt_f32_i32_e32 v144, v144
	v_sub_u32_e32 v3, 32, v3
	v_ffbh_i32_e32 v145, v195
	v_add_u32_e32 v145, -1, v145
	v_ldexp_f32 v3, v144, v3
	v_xor_b32_e32 v144, v194, v195
	v_ashrrev_i32_e32 v144, 31, v144
	v_add_u32_e32 v144, 32, v144
	v_min_u32_e32 v144, v145, v144
	v_lshlrev_b64 v[194:195], v144, v[194:195]
	v_min_u32_e32 v194, 1, v194
	v_or_b32_e32 v194, v195, v194
	v_cvt_f32_i32_e32 v194, v194
	v_mul_f32_e32 v3, 0x33800000, v3
	v_fmamk_f32 v3, v3, 0x3a800000, v223
	v_sub_u32_e32 v195, 32, v144
	v_ldexp_f32 v194, v194, v195
	v_rcp_f32_e32 v195, v3
	v_mul_f32_e32 v194, 0x33800000, v194
	v_fmamk_f32 v194, v194, 0x3a800000, v223
	v_mul_f32_e32 v194, v194, v195
	v_sqrt_f32_e32 v194, v194
	s_nop 0
	v_pk_mul_f32 v[66:67], v[66:67], v[194:195] op_sel_hi:[1,0]
	v_pk_mul_f32 v[64:65], v[64:65], v[194:195] op_sel_hi:[1,0]
	v_pk_mul_f32 v[62:63], v[62:63], v[194:195] op_sel_hi:[1,0]
	v_pk_mul_f32 v[60:61], v[60:61], v[194:195] op_sel_hi:[1,0]
	v_pk_mul_f32 v[58:59], v[58:59], v[194:195] op_sel_hi:[1,0]
	v_pk_mul_f32 v[56:57], v[56:57], v[194:195] op_sel_hi:[1,0]
	v_pk_mul_f32 v[54:55], v[54:55], v[194:195] op_sel_hi:[1,0]
	v_pk_mul_f32 v[52:53], v[52:53], v[194:195] op_sel_hi:[1,0]
	v_xor_b32_e32 v153, v146, v147
	v_ashrrev_i32_e32 v153, 31, v153
	v_ffbh_i32_e32 v202, v147
; __device__ __forceinline__ float fx_get(const long long* p, float inv) { return (float)(*(const GAS long long*)p) * inv; }
;     __device__ __forceinline__ void mid(f32x4 (&acc)[2][2][4][2], const pg8::Unit& u, int wr, int fr) const {
;         const int row0 = u.pm * 256 + wr * 64 + fr;
; #pragma unroll
;         for (int ai = 0; ai < 2; ++ai)
; #pragma unroll
;             for (int m = 0; m < 4; ++m) { int r = row0 + ai * 128 + m * 16; asm volatile("" : "+v"(r));
;                 const float a = fx_get(rs2 + r, FX_RS_INV) * (1.0f / 1024.0f) + RMS_EPS, b = fx_get(rs2 + SEQ + r, FX_RS_INV) * (1.0f / 1024.0f) + RMS_EPS;
;                 const float ratio = __builtin_amdgcn_sqrtf(b * __builtin_amdgcn_rcpf(a));
; #pragma unroll
;                 for (int bj = 0; bj < 2; ++bj)
; #pragma unroll
;                     for (int n = 0; n < 2; ++n) acc[ai][bj][m][n] *= ratio; }
	v_add_u32_e32 v153, 32, v153
	v_add_u32_e32 v202, -1, v202
	v_min_u32_e32 v153, v202, v153
	v_lshlrev_b64 v[146:147], v153, v[146:147]
	v_min_u32_e32 v146, 1, v146
	v_or_b32_e32 v146, v147, v146
	v_cvt_f32_i32_e32 v146, v146
	v_sub_u32_e32 v153, 32, v153
	v_ffbh_i32_e32 v147, v197
	v_add_u32_e32 v147, -1, v147
	v_ldexp_f32 v153, v146, v153
	v_xor_b32_e32 v146, v196, v197
	v_ashrrev_i32_e32 v146, 31, v146
	v_add_u32_e32 v146, 32, v146
	v_min_u32_e32 v146, v147, v146
	v_lshlrev_b64 v[196:197], v146, v[196:197]
	v_min_u32_e32 v196, 1, v196
	v_or_b32_e32 v196, v197, v196
	v_cvt_f32_i32_e32 v196, v196
	v_mul_f32_e32 v153, 0x33800000, v153
	v_fmamk_f32 v153, v153, 0x3a800000, v223
	v_sub_u32_e32 v197, 32, v146
	v_ldexp_f32 v196, v196, v197
	v_rcp_f32_e32 v197, v153
	v_mul_f32_e32 v196, 0x33800000, v196
	v_fmamk_f32 v196, v196, 0x3a800000, v223
	v_mul_f32_e32 v196, v196, v197
	v_sqrt_f32_e32 v196, v196
	s_nop 0
	v_pk_mul_f32 v[50:51], v[50:51], v[196:197] op_sel_hi:[1,0]
	v_pk_mul_f32 v[48:49], v[48:49], v[196:197] op_sel_hi:[1,0]
	v_pk_mul_f32 v[46:47], v[46:47], v[196:197] op_sel_hi:[1,0]
	v_pk_mul_f32 v[44:45], v[44:45], v[196:197] op_sel_hi:[1,0]
	v_pk_mul_f32 v[42:43], v[42:43], v[196:197] op_sel_hi:[1,0]
	v_pk_mul_f32 v[40:41], v[40:41], v[196:197] op_sel_hi:[1,0]
	v_pk_mul_f32 v[38:39], v[38:39], v[196:197] op_sel_hi:[1,0]
	v_pk_mul_f32 v[36:37], v[36:37], v[196:197] op_sel_hi:[1,0]
	v_xor_b32_e32 v3, v148, v149
	v_ashrrev_i32_e32 v3, 31, v3
	v_ffbh_i32_e32 v152, v149
	v_add_u32_e32 v3, 32, v3
	v_add_u32_e32 v152, -1, v152
	v_min_u32_e32 v3, v152, v3
	v_lshlrev_b64 v[148:149], v3, v[148:149]
	v_min_u32_e32 v148, 1, v148
	v_or_b32_e32 v148, v149, v148
	v_cvt_f32_i32_e32 v148, v148
	v_sub_u32_e32 v3, 32, v3
	v_ffbh_i32_e32 v149, v199
	v_add_u32_e32 v149, -1, v149
	v_ldexp_f32 v3, v148, v3
	v_xor_b32_e32 v148, v198, v199
	v_ashrrev_i32_e32 v148, 31, v148
	v_add_u32_e32 v148, 32, v148
	v_min_u32_e32 v148, v149, v148
	v_lshlrev_b64 v[198:199], v148, v[198:199]
	v_min_u32_e32 v198, 1, v198
	v_or_b32_e32 v198, v199, v198
	v_cvt_f32_i32_e32 v198, v198
	v_mul_f32_e32 v3, 0x33800000, v3
	v_fmamk_f32 v3, v3, 0x3a800000, v223
	v_sub_u32_e32 v199, 32, v148
	v_ldexp_f32 v198, v198, v199
	v_rcp_f32_e32 v199, v3
	v_mul_f32_e32 v198, 0x33800000, v198
	v_fmamk_f32 v198, v198, 0x3a800000, v223
	v_mul_f32_e32 v198, v198, v199
	v_sqrt_f32_e32 v198, v198
	s_nop 0
	v_pk_mul_f32 v[34:35], v[34:35], v[198:199] op_sel_hi:[1,0]
	v_pk_mul_f32 v[32:33], v[32:33], v[198:199] op_sel_hi:[1,0]
	v_pk_mul_f32 v[30:31], v[30:31], v[198:199] op_sel_hi:[1,0]
	v_pk_mul_f32 v[28:29], v[28:29], v[198:199] op_sel_hi:[1,0]
	v_pk_mul_f32 v[26:27], v[26:27], v[198:199] op_sel_hi:[1,0]
	v_pk_mul_f32 v[24:25], v[24:25], v[198:199] op_sel_hi:[1,0]
	v_pk_mul_f32 v[22:23], v[22:23], v[198:199] op_sel_hi:[1,0]
	v_pk_mul_f32 v[20:21], v[20:21], v[198:199] op_sel_hi:[1,0]
	v_xor_b32_e32 v153, v150, v151
	v_ashrrev_i32_e32 v153, 31, v153
	v_ffbh_i32_e32 v202, v151
	v_add_u32_e32 v153, 32, v153
	v_add_u32_e32 v202, -1, v202
	v_min_u32_e32 v153, v202, v153
	v_lshlrev_b64 v[150:151], v153, v[150:151]
	v_min_u32_e32 v150, 1, v150
	v_or_b32_e32 v150, v151, v150
	v_cvt_f32_i32_e32 v150, v150
	v_sub_u32_e32 v153, 32, v153
	v_ffbh_i32_e32 v151, v201
	v_add_u32_e32 v151, -1, v151
	v_ldexp_f32 v153, v150, v153
	v_xor_b32_e32 v150, v200, v201
	v_ashrrev_i32_e32 v150, 31, v150
	v_add_u32_e32 v150, 32, v150
	v_min_u32_e32 v150, v151, v150
	v_lshlrev_b64 v[200:201], v150, v[200:201]
	v_min_u32_e32 v200, 1, v200
	v_or_b32_e32 v200, v201, v200
	v_cvt_f32_i32_e32 v200, v200
	v_mul_f32_e32 v153, 0x33800000, v153
	v_fmamk_f32 v153, v153, 0x3a800000, v223
	v_sub_u32_e32 v201, 32, v150
	v_ldexp_f32 v200, v200, v201
	v_rcp_f32_e32 v201, v153
	v_mul_f32_e32 v200, 0x33800000, v200
	v_fmamk_f32 v200, v200, 0x3a800000, v223
	v_mul_f32_e32 v200, v200, v201
	v_sqrt_f32_e32 v200, v200
	s_nop 0
	v_pk_mul_f32 v[18:19], v[18:19], v[200:201] op_sel_hi:[1,0]
	v_pk_mul_f32 v[16:17], v[16:17], v[200:201] op_sel_hi:[1,0]
	v_pk_mul_f32 v[14:15], v[14:15], v[200:201] op_sel_hi:[1,0]
	v_pk_mul_f32 v[12:13], v[12:13], v[200:201] op_sel_hi:[1,0]
	v_pk_mul_f32 v[10:11], v[10:11], v[200:201] op_sel_hi:[1,0]
	v_pk_mul_f32 v[8:9], v[8:9], v[200:201] op_sel_hi:[1,0]
	v_pk_mul_f32 v[6:7], v[6:7], v[200:201] op_sel_hi:[1,0]
	v_pk_mul_f32 v[4:5], v[4:5], v[200:201] op_sel_hi:[1,0]

; #define GAS __attribute__((address_space(1)))
; __device__ __forceinline__ float fx_get(const long long* p, float inv) { return (float)(*(const GAS long long*)p) * inv; }
;     template <bool XF32> __device__ __forceinline__ void store_res(const f32x4 (&acc)[2][2][4][2], const pg8::Unit& u, int wr, int wc, int fr, int fq) const {
;     ...
;         f32x4 gv[2][2];
; #pragma unroll
;         for (int bj = 0; bj < 2; ++bj)
; #pragma unroll
;             for (int n = 0; n < 2; ++n) gv[bj][n] = *(const GAS f32x4*)(gate + col0 + bj * 128 + n * 4) + 1.0f;
; #pragma unroll
;         for (int ai = 0; ai < 2; ++ai) {
;             float rsc[4];
; #pragma unroll
;             for (int m = 0; m < 4; ++m) rsc[m] = rs2 ? __builtin_amdgcn_rsqf(fx_get(rs2 + SEQ + row0 + ai * 128 + m * 16, FX_RS_INV) * (1.0f / 1024.0f) + RMS_EPS) : 1.0f;
.LBB0_433:
	v_ashrrev_i32_e32 v1, 31, v0
	v_lshl_add_u64 v[140:141], v[0:1], 2, s[12:13]
	global_load_dwordx4 v[132:135], v[140:141], off offset:16
	global_load_dwordx4 v[136:139], v[140:141], off
	v_cndmask_b32_e64 v3, 0, 1, s[24:25]
	s_andn2_b64 vcc, exec, s[28:29]
	v_cmp_ne_u32_e64 s[4:5], 1, v3
	s_waitcnt vmcnt(0)
	v_pk_add_f32 v[190:191], v[134:135], 1.0 op_sel_hi:[1,0]
	v_pk_add_f32 v[198:199], v[138:139], 1.0 op_sel_hi:[1,0]
	v_pk_add_f32 v[200:201], v[136:137], 1.0 op_sel_hi:[1,0]
	v_pk_add_f32 v[192:193], v[132:133], 1.0 op_sel_hi:[1,0]
	global_load_dwordx4 v[132:135], v[140:141], off offset:528
	global_load_dwordx4 v[136:139], v[140:141], off offset:512
	s_waitcnt vmcnt(0)
	v_pk_add_f32 v[186:187], v[134:135], 1.0 op_sel_hi:[1,0]
	v_pk_add_f32 v[194:195], v[138:139], 1.0 op_sel_hi:[1,0]
	v_pk_add_f32 v[196:197], v[136:137], 1.0 op_sel_hi:[1,0]
	v_pk_add_f32 v[188:189], v[132:133], 1.0 op_sel_hi:[1,0]
	v_lshl_add_u64 v[132:133], v[184:185], 3, s[26:27]
	s_cbranch_vccnz .LBB0_452
	v_mov_b64_e32 v[250:251], v[132:133]
	v_mov_b32_e32 v132, 1.0
	v_mov_b32_e32 v134, 1.0
	v_mov_b32_e32 v136, 1.0
	v_mov_b32_e32 v138, 1.0
	v_mov_b32_e32 v140, 1.0
	v_mov_b32_e32 v212, 1.0
	v_mov_b32_e32 v214, 1.0
	v_mov_b32_e32 v216, 1.0
	s_and_b64 vcc, exec, s[4:5]
	s_cbranch_vccnz .Lmy_xf_nors
	global_load_dwordx2 v[230:231], v[250:251], off
	global_load_dwordx2 v[232:233], v[250:251], off offset:128
	global_load_dwordx2 v[234:235], v[250:251], off offset:256
	global_load_dwordx2 v[236:237], v[250:251], off offset:384
	global_load_dwordx2 v[238:239], v[250:251], off offset:1024
	global_load_dwordx2 v[240:241], v[250:251], off offset:1152
	global_load_dwordx2 v[242:243], v[250:251], off offset:1280
	global_load_dwordx2 v[244:245], v[250:251], off offset:1408
	s_waitcnt vmcnt(0)
	v_xor_b32_e32 v142, v230, v231
	v_ffbh_i32_e32 v143, v231
	v_ashrrev_i32_e32 v142, 31, v142
	v_add_u32_e32 v143, -1, v143
	v_add_u32_e32 v142, 32, v142
	v_min_u32_e32 v143, v143, v142
	v_lshlrev_b64 v[230:231], v143, v[230:231]
	v_min_u32_e32 v230, 1, v230
	v_or_b32_e32 v230, v231, v230
	v_cvt_f32_i32_e32 v230, v230
	v_sub_u32_e32 v143, 32, v143
	v_ldexp_f32 v143, v230, v143
	v_mul_f32_e32 v143, 0x33800000, v143
	v_fmamk_f32 v143, v143, 0x3a800000, v223
	v_rsq_f32_e32 v132, v143
	v_xor_b32_e32 v144, v232, v233
	v_ffbh_i32_e32 v145, v233
	v_ashrrev_i32_e32 v144, 31, v144
	v_add_u32_e32 v145, -1, v145
	v_add_u32_e32 v144, 32, v144
	v_min_u32_e32 v145, v145, v144
	v_lshlrev_b64 v[232:233], v145, v[232:233]
	v_min_u32_e32 v232, 1, v232
	v_or_b32_e32 v232, v233, v232
	v_cvt_f32_i32_e32 v232, v232
	v_sub_u32_e32 v145, 32, v145
	v_ldexp_f32 v145, v232, v145
	v_mul_f32_e32 v145, 0x33800000, v145
	v_fmamk_f32 v145, v145, 0x3a800000, v223
	v_rsq_f32_e32 v134, v145
	v_xor_b32_e32 v142, v234, v235
	v_ffbh_i32_e32 v143, v235
	v_ashrrev_i32_e32 v142, 31, v142
	v_add_u32_e32 v143, -1, v143
	v_add_u32_e32 v142, 32, v142
	v_min_u32_e32 v143, v143, v142
	v_lshlrev_b64 v[234:235], v143, v[234:235]
	v_min_u32_e32 v234, 1, v234
	v_or_b32_e32 v234, v235, v234
	v_cvt_f32_i32_e32 v234, v234
	v_sub_u32_e32 v143, 32, v143
	v_ldexp_f32 v143, v234, v143
	v_mul_f32_e32 v143, 0x33800000, v143
	v_fmamk_f32 v143, v143, 0x3a800000, v223
	v_rsq_f32_e32 v136, v143
	v_xor_b32_e32 v144, v236, v237
	v_ffbh_i32_e32 v145, v237
	v_ashrrev_i32_e32 v144, 31, v144
	v_add_u32_e32 v145, -1, v145
	v_add_u32_e32 v144, 32, v144
	v_min_u32_e32 v145, v145, v144
	v_lshlrev_b64 v[236:237], v145, v[236:237]
	v_min_u32_e32 v236, 1, v236
	v_or_b32_e32 v236, v237, v236
	v_cvt_f32_i32_e32 v236, v236
	v_sub_u32_e32 v145, 32, v145
	v_ldexp_f32 v145, v236, v145
	v_mul_f32_e32 v145, 0x33800000, v145
	v_fmamk_f32 v145, v145, 0x3a800000, v223
	v_rsq_f32_e32 v138, v145
	v_xor_b32_e32 v142, v238, v239
	v_ffbh_i32_e32 v143, v239
	v_ashrrev_i32_e32 v142, 31, v142
	v_add_u32_e32 v143, -1, v143
	v_add_u32_e32 v142, 32, v142
	v_min_u32_e32 v143, v143, v142
	v_lshlrev_b64 v[238:239], v143, v[238:239]
	v_min_u32_e32 v238, 1, v238
	v_or_b32_e32 v238, v239, v238
	v_cvt_f32_i32_e32 v238, v238
	v_sub_u32_e32 v143, 32, v143
	v_ldexp_f32 v143, v238, v143
	v_mul_f32_e32 v143, 0x33800000, v143
	v_fmamk_f32 v143, v143, 0x3a800000, v223
	v_rsq_f32_e32 v140, v143
	v_xor_b32_e32 v144, v240, v241
	v_ffbh_i32_e32 v145, v241
	v_ashrrev_i32_e32 v144, 31, v144
	v_add_u32_e32 v145, -1, v145
	v_add_u32_e32 v144, 32, v144
	v_min_u32_e32 v145, v145, v144
	v_lshlrev_b64 v[240:241], v145, v[240:241]
	v_min_u32_e32 v240, 1, v240
	v_or_b32_e32 v240, v241, v240
	v_cvt_f32_i32_e32 v240, v240
	v_sub_u32_e32 v145, 32, v145
	v_ldexp_f32 v145, v240, v145
	v_mul_f32_e32 v145, 0x33800000, v145
	v_fmamk_f32 v145, v145, 0x3a800000, v223
	v_rsq_f32_e32 v212, v145
	v_xor_b32_e32 v142, v242, v243
	v_ffbh_i32_e32 v143, v243
	v_ashrrev_i32_e32 v142, 31, v142
	v_add_u32_e32 v143, -1, v143
	v_add_u32_e32 v142, 32, v142
	v_min_u32_e32 v143, v143, v142
	v_lshlrev_b64 v[242:243], v143, v[242:243]
	v_min_u32_e32 v242, 1, v242
	v_or_b32_e32 v242, v243, v242
	v_cvt_f32_i32_e32 v242, v242
	v_sub_u32_e32 v143, 32, v143
	v_ldexp_f32 v143, v242, v143
	v_mul_f32_e32 v143, 0x33800000, v143
	v_fmamk_f32 v143, v143, 0x3a800000, v223
	v_rsq_f32_e32 v214, v143
	v_xor_b32_e32 v144, v244, v245
	v_ffbh_i32_e32 v145, v245
	v_ashrrev_i32_e32 v144, 31, v144
	v_add_u32_e32 v145, -1, v145
	v_add_u32_e32 v144, 32, v144
	v_min_u32_e32 v145, v145, v144
	v_lshlrev_b64 v[244:245], v145, v[244:245]
	v_min_u32_e32 v244, 1, v244
	v_or_b32_e32 v244, v245, v244
	v_cvt_f32_i32_e32 v244, v244
	v_sub_u32_e32 v145, 32, v145
	v_ldexp_f32 v145, v244, v145
	v_mul_f32_e32 v145, 0x33800000, v145
	v_fmamk_f32 v145, v145, 0x3a800000, v223
	v_rsq_f32_e32 v216, v145
; #define GAS __attribute__((address_space(1)))
; __device__ __forceinline__ unsigned cvt_pk_bf16(float lo, float hi) { const f32x2 v = {lo, hi}; const bf16x2_t b = __builtin_convertvector(v, bf16x2_t); return __builtin_bit_cast(unsigned, b); }
;     template <bool XF32> __device__ __forceinline__ void store_res(const f32x4 (&acc)[2][2][4][2], const pg8::Unit& u, int wr, int wc, int fr, int fq) const {
;     ...
; #pragma unroll
;             for (int m = 0; m < 4; ++m) { const size_t off = (size_t)(row0 + ai * 128 + m * 16) * DM + col0;
; #pragma unroll
;                 for (int bj = 0; bj < 2; ++bj) { f32x4 x0, x1;
;                     if (XF32) { x0 = *(const GAS f32x4*)(xin + off + bj * 128); x1 = *(const GAS f32x4*)(xin + off + bj * 128 + 4); }
;                     else { const u32x4 xb = xpre[m][bj];
;                         x0 = (f32x4){bf2f((unsigned short)(xb.x & 0xffff)), bf2f((unsigned short)(xb.x >> 16)), bf2f((unsigned short)(xb.y & 0xffff)), bf2f((unsigned short)(xb.y >> 16))};
;                         x1 = (f32x4){bf2f((unsigned short)(xb.z & 0xffff)), bf2f((unsigned short)(xb.z >> 16)), bf2f((unsigned short)(xb.w & 0xffff)), bf2f((unsigned short)(xb.w >> 16))}; }
;                     const f32x4 z0 = ALPHA * x0 + gv[bj][0] * (acc[ai][bj][m][0] * rsc[m]), z1 = ALPHA * x1 + gv[bj][1] * (acc[ai][bj][m][1] * rsc[m]);
;                     u32x4 w; w.x = cvt_pk_bf16(z0[0], z0[1]); w.y = cvt_pk_bf16(z0[2], z0[3]); w.z = cvt_pk_bf16(z1[0], z1[1]); w.w = cvt_pk_bf16(z1[2], z1[3]);
;                     *(GAS u32x4*)(O + off + bj * 128) = w; }
;                 if (XF32) asm volatile("" ::: "memory"); } }
.Lmy_xf_nors:
	v_lshlrev_b64 v[150:151], 11, v[184:185]
	v_lshl_add_u64 v[150:151], v[150:151], 0, v[0:1]
	v_lshl_add_u64 v[250:251], v[150:151], 2, s[14:15]
	v_lshl_add_u64 v[154:155], v[150:151], 1, s[10:11]
	s_mov_b32 s36, 0x20000
	s_mov_b32 s37, 0
	s_mov_b32 s34, 0x10000
	s_mov_b32 s35, 0
	global_load_dwordx4 v[230:233], v[250:251], off
	global_load_dwordx4 v[234:237], v[250:251], off offset:16
	global_load_dwordx4 v[238:241], v[250:251], off offset:512
	global_load_dwordx4 v[242:245], v[250:251], off offset:528
	v_lshl_add_u64 v[250:251], v[250:251], 0, s[36:37]
	global_load_dwordx4 v[246:249], v[250:251], off
	global_load_dwordx4 v[218:221], v[250:251], off offset:16
	global_load_dwordx4 v[142:145], v[250:251], off offset:512
	global_load_dwordx4 v[146:149], v[250:251], off offset:528
	s_waitcnt vmcnt(4)
	v_pk_mul_f32 v[150:151], v[128:129], v[132:133] op_sel_hi:[1,0]
	v_pk_mul_f32 v[230:231], v[230:231], s[96:97] op_sel_hi:[1,0]
	v_pk_fma_f32 v[230:231], v[200:201], v[150:151], v[230:231]
	v_pk_mul_f32 v[152:153], v[130:131], v[132:133] op_sel_hi:[1,0]
	v_pk_mul_f32 v[232:233], v[232:233], s[96:97] op_sel_hi:[1,0]
	v_pk_fma_f32 v[232:233], v[198:199], v[152:153], v[232:233]
	v_pk_mul_f32 v[150:151], v[124:125], v[132:133] op_sel_hi:[1,0]
	v_pk_mul_f32 v[234:235], v[234:235], s[96:97] op_sel_hi:[1,0]
	v_pk_fma_f32 v[234:235], v[192:193], v[150:151], v[234:235]
	v_pk_mul_f32 v[152:153], v[126:127], v[132:133] op_sel_hi:[1,0]
	v_pk_mul_f32 v[236:237], v[236:237], s[96:97] op_sel_hi:[1,0]
	v_pk_fma_f32 v[236:237], v[190:191], v[152:153], v[236:237]
	v_cvt_pk_bf16_f32 v230, v230, v231
	v_cvt_pk_bf16_f32 v231, v232, v233
	v_cvt_pk_bf16_f32 v232, v234, v235
	v_cvt_pk_bf16_f32 v233, v236, v237
	global_store_dwordx4 v[154:155], v[230:233], off
	v_pk_mul_f32 v[150:151], v[120:121], v[132:133] op_sel_hi:[1,0]
	v_pk_mul_f32 v[238:239], v[238:239], s[96:97] op_sel_hi:[1,0]
	v_pk_fma_f32 v[238:239], v[196:197], v[150:151], v[238:239]
	v_pk_mul_f32 v[152:153], v[122:123], v[132:133] op_sel_hi:[1,0]
	v_pk_mul_f32 v[240:241], v[240:241], s[96:97] op_sel_hi:[1,0]
	v_pk_fma_f32 v[240:241], v[194:195], v[152:153], v[240:241]
	v_pk_mul_f32 v[150:151], v[116:117], v[132:133] op_sel_hi:[1,0]
	v_pk_mul_f32 v[242:243], v[242:243], s[96:97] op_sel_hi:[1,0]
	v_pk_fma_f32 v[242:243], v[188:189], v[150:151], v[242:243]
	v_pk_mul_f32 v[152:153], v[118:119], v[132:133] op_sel_hi:[1,0]
	v_pk_mul_f32 v[244:245], v[244:245], s[96:97] op_sel_hi:[1,0]
	v_pk_fma_f32 v[244:245], v[186:187], v[152:153], v[244:245]
	v_cvt_pk_bf16_f32 v238, v238, v239
	v_cvt_pk_bf16_f32 v239, v240, v241
	v_cvt_pk_bf16_f32 v240, v242, v243
	v_cvt_pk_bf16_f32 v241, v244, v245
	global_store_dwordx4 v[154:155], v[238:241], off offset:256
	v_lshl_add_u64 v[154:155], v[154:155], 0, s[34:35]
	v_lshl_add_u64 v[250:251], v[250:251], 0, s[36:37]
	global_load_dwordx4 v[230:233], v[250:251], off
	global_load_dwordx4 v[234:237], v[250:251], off offset:16
	global_load_dwordx4 v[238:241], v[250:251], off offset:512
	global_load_dwordx4 v[242:245], v[250:251], off offset:528
	s_waitcnt vmcnt(6)
	v_pk_mul_f32 v[150:151], v[112:113], v[134:135] op_sel_hi:[1,0]
	v_pk_mul_f32 v[246:247], v[246:247], s[96:97] op_sel_hi:[1,0]
	v_pk_fma_f32 v[246:247], v[200:201], v[150:151], v[246:247]
	v_pk_mul_f32 v[152:153], v[114:115], v[134:135] op_sel_hi:[1,0]
	v_pk_mul_f32 v[248:249], v[248:249], s[96:97] op_sel_hi:[1,0]
	v_pk_fma_f32 v[248:249], v[198:199], v[152:153], v[248:249]
	v_pk_mul_f32 v[150:151], v[108:109], v[134:135] op_sel_hi:[1,0]
	v_pk_mul_f32 v[218:219], v[218:219], s[96:97] op_sel_hi:[1,0]
	v_pk_fma_f32 v[218:219], v[192:193], v[150:151], v[218:219]
	v_pk_mul_f32 v[152:153], v[110:111], v[134:135] op_sel_hi:[1,0]
	v_pk_mul_f32 v[220:221], v[220:221], s[96:97] op_sel_hi:[1,0]
	v_pk_fma_f32 v[220:221], v[190:191], v[152:153], v[220:221]
	v_cvt_pk_bf16_f32 v246, v246, v247
	v_cvt_pk_bf16_f32 v247, v248, v249
	v_cvt_pk_bf16_f32 v248, v218, v219
	v_cvt_pk_bf16_f32 v249, v220, v221
	global_store_dwordx4 v[154:155], v[246:249], off
	v_pk_mul_f32 v[150:151], v[104:105], v[134:135] op_sel_hi:[1,0]
	v_pk_mul_f32 v[142:143], v[142:143], s[96:97] op_sel_hi:[1,0]
	v_pk_fma_f32 v[142:143], v[196:197], v[150:151], v[142:143]
	v_pk_mul_f32 v[152:153], v[106:107], v[134:135] op_sel_hi:[1,0]
	v_pk_mul_f32 v[144:145], v[144:145], s[96:97] op_sel_hi:[1,0]
	v_pk_fma_f32 v[144:145], v[194:195], v[152:153], v[144:145]
	v_pk_mul_f32 v[150:151], v[100:101], v[134:135] op_sel_hi:[1,0]
	v_pk_mul_f32 v[146:147], v[146:147], s[96:97] op_sel_hi:[1,0]
	v_pk_fma_f32 v[146:147], v[188:189], v[150:151], v[146:147]
	v_pk_mul_f32 v[152:153], v[102:103], v[134:135] op_sel_hi:[1,0]
	v_pk_mul_f32 v[148:149], v[148:149], s[96:97] op_sel_hi:[1,0]
	v_pk_fma_f32 v[148:149], v[186:187], v[152:153], v[148:149]
	v_cvt_pk_bf16_f32 v142, v142, v143
	v_cvt_pk_bf16_f32 v143, v144, v145
	v_cvt_pk_bf16_f32 v144, v146, v147
	v_cvt_pk_bf16_f32 v145, v148, v149
	global_store_dwordx4 v[154:155], v[142:145], off offset:256
	v_lshl_add_u64 v[154:155], v[154:155], 0, s[34:35]
	v_lshl_add_u64 v[250:251], v[250:251], 0, s[36:37]
	global_load_dwordx4 v[246:249], v[250:251], off
	global_load_dwordx4 v[218:221], v[250:251], off offset:16
	global_load_dwordx4 v[142:145], v[250:251], off offset:512
	global_load_dwordx4 v[146:149], v[250:251], off offset:528
	s_waitcnt vmcnt(6)
; #define GAS __attribute__((address_space(1)))
; __device__ __forceinline__ unsigned cvt_pk_bf16(float lo, float hi) { const f32x2 v = {lo, hi}; const bf16x2_t b = __builtin_convertvector(v, bf16x2_t); return __builtin_bit_cast(unsigned, b); }
;     template <bool XF32> __device__ __forceinline__ void store_res(const f32x4 (&acc)[2][2][4][2], const pg8::Unit& u, int wr, int wc, int fr, int fq) const {
;     ...
; #pragma unroll
;             for (int m = 0; m < 4; ++m) { const size_t off = (size_t)(row0 + ai * 128 + m * 16) * DM + col0;
; #pragma unroll
;                 for (int bj = 0; bj < 2; ++bj) { f32x4 x0, x1;
;                     if (XF32) { x0 = *(const GAS f32x4*)(xin + off + bj * 128); x1 = *(const GAS f32x4*)(xin + off + bj * 128 + 4); }
;                     else { const u32x4 xb = xpre[m][bj];
;                         x0 = (f32x4){bf2f((unsigned short)(xb.x & 0xffff)), bf2f((unsigned short)(xb.x >> 16)), bf2f((unsigned short)(xb.y & 0xffff)), bf2f((unsigned short)(xb.y >> 16))};
;                         x1 = (f32x4){bf2f((unsigned short)(xb.z & 0xffff)), bf2f((unsigned short)(xb.z >> 16)), bf2f((unsigned short)(xb.w & 0xffff)), bf2f((unsigned short)(xb.w >> 16))}; }
;                     const f32x4 z0 = ALPHA * x0 + gv[bj][0] * (acc[ai][bj][m][0] * rsc[m]), z1 = ALPHA * x1 + gv[bj][1] * (acc[ai][bj][m][1] * rsc[m]);
;                     u32x4 w; w.x = cvt_pk_bf16(z0[0], z0[1]); w.y = cvt_pk_bf16(z0[2], z0[3]); w.z = cvt_pk_bf16(z1[0], z1[1]); w.w = cvt_pk_bf16(z1[2], z1[3]);
;                     *(GAS u32x4*)(O + off + bj * 128) = w; }
;                 if (XF32) asm volatile("" ::: "memory"); } }
	v_pk_mul_f32 v[150:151], v[96:97], v[136:137] op_sel_hi:[1,0]
	v_pk_mul_f32 v[230:231], v[230:231], s[96:97] op_sel_hi:[1,0]
	v_pk_fma_f32 v[230:231], v[200:201], v[150:151], v[230:231]
	v_pk_mul_f32 v[152:153], v[98:99], v[136:137] op_sel_hi:[1,0]
	v_pk_mul_f32 v[232:233], v[232:233], s[96:97] op_sel_hi:[1,0]
	v_pk_fma_f32 v[232:233], v[198:199], v[152:153], v[232:233]
	v_pk_mul_f32 v[150:151], v[92:93], v[136:137] op_sel_hi:[1,0]
	v_pk_mul_f32 v[234:235], v[234:235], s[96:97] op_sel_hi:[1,0]
	v_pk_fma_f32 v[234:235], v[192:193], v[150:151], v[234:235]
	v_pk_mul_f32 v[152:153], v[94:95], v[136:137] op_sel_hi:[1,0]
	v_pk_mul_f32 v[236:237], v[236:237], s[96:97] op_sel_hi:[1,0]
	v_pk_fma_f32 v[236:237], v[190:191], v[152:153], v[236:237]
	v_cvt_pk_bf16_f32 v230, v230, v231
	v_cvt_pk_bf16_f32 v231, v232, v233
	v_cvt_pk_bf16_f32 v232, v234, v235
	v_cvt_pk_bf16_f32 v233, v236, v237
	global_store_dwordx4 v[154:155], v[230:233], off
	v_pk_mul_f32 v[150:151], v[88:89], v[136:137] op_sel_hi:[1,0]
	v_pk_mul_f32 v[238:239], v[238:239], s[96:97] op_sel_hi:[1,0]
	v_pk_fma_f32 v[238:239], v[196:197], v[150:151], v[238:239]
	v_pk_mul_f32 v[152:153], v[90:91], v[136:137] op_sel_hi:[1,0]
	v_pk_mul_f32 v[240:241], v[240:241], s[96:97] op_sel_hi:[1,0]
	v_pk_fma_f32 v[240:241], v[194:195], v[152:153], v[240:241]
	v_pk_mul_f32 v[150:151], v[84:85], v[136:137] op_sel_hi:[1,0]
	v_pk_mul_f32 v[242:243], v[242:243], s[96:97] op_sel_hi:[1,0]
	v_pk_fma_f32 v[242:243], v[188:189], v[150:151], v[242:243]
	v_pk_mul_f32 v[152:153], v[86:87], v[136:137] op_sel_hi:[1,0]
	v_pk_mul_f32 v[244:245], v[244:245], s[96:97] op_sel_hi:[1,0]
	v_pk_fma_f32 v[244:245], v[186:187], v[152:153], v[244:245]
	v_cvt_pk_bf16_f32 v238, v238, v239
	v_cvt_pk_bf16_f32 v239, v240, v241
	v_cvt_pk_bf16_f32 v240, v242, v243
	v_cvt_pk_bf16_f32 v241, v244, v245
	global_store_dwordx4 v[154:155], v[238:241], off offset:256
	v_lshl_add_u64 v[154:155], v[154:155], 0, s[34:35]
	v_lshl_add_u64 v[250:251], v[250:251], 0, s[36:37]
	v_lshl_add_u64 v[250:251], v[250:251], 0, s[36:37]
	v_lshl_add_u64 v[250:251], v[250:251], 0, s[36:37]
	v_lshl_add_u64 v[250:251], v[250:251], 0, s[36:37]
	v_lshl_add_u64 v[250:251], v[250:251], 0, s[36:37]
	global_load_dwordx4 v[230:233], v[250:251], off
	global_load_dwordx4 v[234:237], v[250:251], off offset:16
	global_load_dwordx4 v[238:241], v[250:251], off offset:512
	global_load_dwordx4 v[242:245], v[250:251], off offset:528
	s_waitcnt vmcnt(6)
	v_pk_mul_f32 v[150:151], v[80:81], v[138:139] op_sel_hi:[1,0]
	v_pk_mul_f32 v[246:247], v[246:247], s[96:97] op_sel_hi:[1,0]
	v_pk_fma_f32 v[246:247], v[200:201], v[150:151], v[246:247]
	v_pk_mul_f32 v[152:153], v[82:83], v[138:139] op_sel_hi:[1,0]
	v_pk_mul_f32 v[248:249], v[248:249], s[96:97] op_sel_hi:[1,0]
	v_pk_fma_f32 v[248:249], v[198:199], v[152:153], v[248:249]
	v_pk_mul_f32 v[150:151], v[76:77], v[138:139] op_sel_hi:[1,0]
	v_pk_mul_f32 v[218:219], v[218:219], s[96:97] op_sel_hi:[1,0]
	v_pk_fma_f32 v[218:219], v[192:193], v[150:151], v[218:219]
	v_pk_mul_f32 v[152:153], v[78:79], v[138:139] op_sel_hi:[1,0]
	v_pk_mul_f32 v[220:221], v[220:221], s[96:97] op_sel_hi:[1,0]
	v_pk_fma_f32 v[220:221], v[190:191], v[152:153], v[220:221]
	v_cvt_pk_bf16_f32 v246, v246, v247
	v_cvt_pk_bf16_f32 v247, v248, v249
	v_cvt_pk_bf16_f32 v248, v218, v219
	v_cvt_pk_bf16_f32 v249, v220, v221
	global_store_dwordx4 v[154:155], v[246:249], off
	v_pk_mul_f32 v[150:151], v[72:73], v[138:139] op_sel_hi:[1,0]
	v_pk_mul_f32 v[142:143], v[142:143], s[96:97] op_sel_hi:[1,0]
	v_pk_fma_f32 v[142:143], v[196:197], v[150:151], v[142:143]
	v_pk_mul_f32 v[152:153], v[74:75], v[138:139] op_sel_hi:[1,0]
	v_pk_mul_f32 v[144:145], v[144:145], s[96:97] op_sel_hi:[1,0]
	v_pk_fma_f32 v[144:145], v[194:195], v[152:153], v[144:145]
	v_pk_mul_f32 v[150:151], v[68:69], v[138:139] op_sel_hi:[1,0]
	v_pk_mul_f32 v[146:147], v[146:147], s[96:97] op_sel_hi:[1,0]
	v_pk_fma_f32 v[146:147], v[188:189], v[150:151], v[146:147]
	v_pk_mul_f32 v[152:153], v[70:71], v[138:139] op_sel_hi:[1,0]
	v_pk_mul_f32 v[148:149], v[148:149], s[96:97] op_sel_hi:[1,0]
	v_pk_fma_f32 v[148:149], v[186:187], v[152:153], v[148:149]
	v_cvt_pk_bf16_f32 v142, v142, v143
	v_cvt_pk_bf16_f32 v143, v144, v145
	v_cvt_pk_bf16_f32 v144, v146, v147
	v_cvt_pk_bf16_f32 v145, v148, v149
	global_store_dwordx4 v[154:155], v[142:145], off offset:256
	v_lshl_add_u64 v[154:155], v[154:155], 0, s[34:35]
	v_lshl_add_u64 v[154:155], v[154:155], 0, s[34:35]
	v_lshl_add_u64 v[154:155], v[154:155], 0, s[34:35]
	v_lshl_add_u64 v[154:155], v[154:155], 0, s[34:35]
	v_lshl_add_u64 v[154:155], v[154:155], 0, s[34:35]
	v_lshl_add_u64 v[250:251], v[250:251], 0, s[36:37]
	global_load_dwordx4 v[246:249], v[250:251], off
	global_load_dwordx4 v[218:221], v[250:251], off offset:16
	global_load_dwordx4 v[142:145], v[250:251], off offset:512
	global_load_dwordx4 v[146:149], v[250:251], off offset:528
	s_waitcnt vmcnt(6)
; #define GAS __attribute__((address_space(1)))
; __device__ __forceinline__ unsigned cvt_pk_bf16(float lo, float hi) { const f32x2 v = {lo, hi}; const bf16x2_t b = __builtin_convertvector(v, bf16x2_t); return __builtin_bit_cast(unsigned, b); }
;     template <bool XF32> __device__ __forceinline__ void store_res(const f32x4 (&acc)[2][2][4][2], const pg8::Unit& u, int wr, int wc, int fr, int fq) const {
;     ...
; #pragma unroll
;             for (int m = 0; m < 4; ++m) { const size_t off = (size_t)(row0 + ai * 128 + m * 16) * DM + col0;
; #pragma unroll
;                 for (int bj = 0; bj < 2; ++bj) { f32x4 x0, x1;
;                     if (XF32) { x0 = *(const GAS f32x4*)(xin + off + bj * 128); x1 = *(const GAS f32x4*)(xin + off + bj * 128 + 4); }
;                     else { const u32x4 xb = xpre[m][bj];
;                         x0 = (f32x4){bf2f((unsigned short)(xb.x & 0xffff)), bf2f((unsigned short)(xb.x >> 16)), bf2f((unsigned short)(xb.y & 0xffff)), bf2f((unsigned short)(xb.y >> 16))};
;                         x1 = (f32x4){bf2f((unsigned short)(xb.z & 0xffff)), bf2f((unsigned short)(xb.z >> 16)), bf2f((unsigned short)(xb.w & 0xffff)), bf2f((unsigned short)(xb.w >> 16))}; }
;                     const f32x4 z0 = ALPHA * x0 + gv[bj][0] * (acc[ai][bj][m][0] * rsc[m]), z1 = ALPHA * x1 + gv[bj][1] * (acc[ai][bj][m][1] * rsc[m]);
;                     u32x4 w; w.x = cvt_pk_bf16(z0[0], z0[1]); w.y = cvt_pk_bf16(z0[2], z0[3]); w.z = cvt_pk_bf16(z1[0], z1[1]); w.w = cvt_pk_bf16(z1[2], z1[3]);
;                     *(GAS u32x4*)(O + off + bj * 128) = w; }
;                 if (XF32) asm volatile("" ::: "memory"); } }
	v_pk_mul_f32 v[150:151], v[64:65], v[140:141] op_sel_hi:[1,0]
	v_pk_mul_f32 v[230:231], v[230:231], s[96:97] op_sel_hi:[1,0]
	v_pk_fma_f32 v[230:231], v[200:201], v[150:151], v[230:231]
	v_pk_mul_f32 v[152:153], v[66:67], v[140:141] op_sel_hi:[1,0]
	v_pk_mul_f32 v[232:233], v[232:233], s[96:97] op_sel_hi:[1,0]
	v_pk_fma_f32 v[232:233], v[198:199], v[152:153], v[232:233]
	v_pk_mul_f32 v[150:151], v[60:61], v[140:141] op_sel_hi:[1,0]
	v_pk_mul_f32 v[234:235], v[234:235], s[96:97] op_sel_hi:[1,0]
	v_pk_fma_f32 v[234:235], v[192:193], v[150:151], v[234:235]
	v_pk_mul_f32 v[152:153], v[62:63], v[140:141] op_sel_hi:[1,0]
	v_pk_mul_f32 v[236:237], v[236:237], s[96:97] op_sel_hi:[1,0]
	v_pk_fma_f32 v[236:237], v[190:191], v[152:153], v[236:237]
	v_cvt_pk_bf16_f32 v230, v230, v231
	v_cvt_pk_bf16_f32 v231, v232, v233
	v_cvt_pk_bf16_f32 v232, v234, v235
	v_cvt_pk_bf16_f32 v233, v236, v237
	global_store_dwordx4 v[154:155], v[230:233], off
	v_pk_mul_f32 v[150:151], v[56:57], v[140:141] op_sel_hi:[1,0]
	v_pk_mul_f32 v[238:239], v[238:239], s[96:97] op_sel_hi:[1,0]
	v_pk_fma_f32 v[238:239], v[196:197], v[150:151], v[238:239]
	v_pk_mul_f32 v[152:153], v[58:59], v[140:141] op_sel_hi:[1,0]
	v_pk_mul_f32 v[240:241], v[240:241], s[96:97] op_sel_hi:[1,0]
	v_pk_fma_f32 v[240:241], v[194:195], v[152:153], v[240:241]
	v_pk_mul_f32 v[150:151], v[52:53], v[140:141] op_sel_hi:[1,0]
	v_pk_mul_f32 v[242:243], v[242:243], s[96:97] op_sel_hi:[1,0]
	v_pk_fma_f32 v[242:243], v[188:189], v[150:151], v[242:243]
	v_pk_mul_f32 v[152:153], v[54:55], v[140:141] op_sel_hi:[1,0]
	v_pk_mul_f32 v[244:245], v[244:245], s[96:97] op_sel_hi:[1,0]
	v_pk_fma_f32 v[244:245], v[186:187], v[152:153], v[244:245]
	v_cvt_pk_bf16_f32 v238, v238, v239
	v_cvt_pk_bf16_f32 v239, v240, v241
	v_cvt_pk_bf16_f32 v240, v242, v243
	v_cvt_pk_bf16_f32 v241, v244, v245
	global_store_dwordx4 v[154:155], v[238:241], off offset:256
	v_lshl_add_u64 v[154:155], v[154:155], 0, s[34:35]
	v_lshl_add_u64 v[250:251], v[250:251], 0, s[36:37]
	global_load_dwordx4 v[230:233], v[250:251], off
	global_load_dwordx4 v[234:237], v[250:251], off offset:16
	global_load_dwordx4 v[238:241], v[250:251], off offset:512
	global_load_dwordx4 v[242:245], v[250:251], off offset:528
	s_waitcnt vmcnt(6)
	v_pk_mul_f32 v[150:151], v[48:49], v[212:213] op_sel_hi:[1,0]
	v_pk_mul_f32 v[246:247], v[246:247], s[96:97] op_sel_hi:[1,0]
	v_pk_fma_f32 v[246:247], v[200:201], v[150:151], v[246:247]
	v_pk_mul_f32 v[152:153], v[50:51], v[212:213] op_sel_hi:[1,0]
	v_pk_mul_f32 v[248:249], v[248:249], s[96:97] op_sel_hi:[1,0]
	v_pk_fma_f32 v[248:249], v[198:199], v[152:153], v[248:249]
	v_pk_mul_f32 v[150:151], v[44:45], v[212:213] op_sel_hi:[1,0]
	v_pk_mul_f32 v[218:219], v[218:219], s[96:97] op_sel_hi:[1,0]
	v_pk_fma_f32 v[218:219], v[192:193], v[150:151], v[218:219]
	v_pk_mul_f32 v[152:153], v[46:47], v[212:213] op_sel_hi:[1,0]
	v_pk_mul_f32 v[220:221], v[220:221], s[96:97] op_sel_hi:[1,0]
	v_pk_fma_f32 v[220:221], v[190:191], v[152:153], v[220:221]
	v_cvt_pk_bf16_f32 v246, v246, v247
	v_cvt_pk_bf16_f32 v247, v248, v249
	v_cvt_pk_bf16_f32 v248, v218, v219
	v_cvt_pk_bf16_f32 v249, v220, v221
	global_store_dwordx4 v[154:155], v[246:249], off
	v_pk_mul_f32 v[150:151], v[40:41], v[212:213] op_sel_hi:[1,0]
	v_pk_mul_f32 v[142:143], v[142:143], s[96:97] op_sel_hi:[1,0]
	v_pk_fma_f32 v[142:143], v[196:197], v[150:151], v[142:143]
	v_pk_mul_f32 v[152:153], v[42:43], v[212:213] op_sel_hi:[1,0]
	v_pk_mul_f32 v[144:145], v[144:145], s[96:97] op_sel_hi:[1,0]
	v_pk_fma_f32 v[144:145], v[194:195], v[152:153], v[144:145]
	v_pk_mul_f32 v[150:151], v[36:37], v[212:213] op_sel_hi:[1,0]
	v_pk_mul_f32 v[146:147], v[146:147], s[96:97] op_sel_hi:[1,0]
	v_pk_fma_f32 v[146:147], v[188:189], v[150:151], v[146:147]
	v_pk_mul_f32 v[152:153], v[38:39], v[212:213] op_sel_hi:[1,0]
	v_pk_mul_f32 v[148:149], v[148:149], s[96:97] op_sel_hi:[1,0]
	v_pk_fma_f32 v[148:149], v[186:187], v[152:153], v[148:149]
	v_cvt_pk_bf16_f32 v142, v142, v143
	v_cvt_pk_bf16_f32 v143, v144, v145
	v_cvt_pk_bf16_f32 v144, v146, v147
	v_cvt_pk_bf16_f32 v145, v148, v149
	global_store_dwordx4 v[154:155], v[142:145], off offset:256
	v_lshl_add_u64 v[154:155], v[154:155], 0, s[34:35]
	v_lshl_add_u64 v[250:251], v[250:251], 0, s[36:37]
	global_load_dwordx4 v[246:249], v[250:251], off
	global_load_dwordx4 v[218:221], v[250:251], off offset:16
	global_load_dwordx4 v[142:145], v[250:251], off offset:512
	global_load_dwordx4 v[146:149], v[250:251], off offset:528
	s_waitcnt vmcnt(6)
; #define GAS __attribute__((address_space(1)))
; __device__ __forceinline__ unsigned cvt_pk_bf16(float lo, float hi) { const f32x2 v = {lo, hi}; const bf16x2_t b = __builtin_convertvector(v, bf16x2_t); return __builtin_bit_cast(unsigned, b); }
;     template <bool XF32> __device__ __forceinline__ void store_res(const f32x4 (&acc)[2][2][4][2], const pg8::Unit& u, int wr, int wc, int fr, int fq) const {
;     ...
; #pragma unroll
;             for (int m = 0; m < 4; ++m) { const size_t off = (size_t)(row0 + ai * 128 + m * 16) * DM + col0;
; #pragma unroll
;                 for (int bj = 0; bj < 2; ++bj) { f32x4 x0, x1;
;                     if (XF32) { x0 = *(const GAS f32x4*)(xin + off + bj * 128); x1 = *(const GAS f32x4*)(xin + off + bj * 128 + 4); }
;                     else { const u32x4 xb = xpre[m][bj];
;                         x0 = (f32x4){bf2f((unsigned short)(xb.x & 0xffff)), bf2f((unsigned short)(xb.x >> 16)), bf2f((unsigned short)(xb.y & 0xffff)), bf2f((unsigned short)(xb.y >> 16))};
;                         x1 = (f32x4){bf2f((unsigned short)(xb.z & 0xffff)), bf2f((unsigned short)(xb.z >> 16)), bf2f((unsigned short)(xb.w & 0xffff)), bf2f((unsigned short)(xb.w >> 16))}; }
;                     const f32x4 z0 = ALPHA * x0 + gv[bj][0] * (acc[ai][bj][m][0] * rsc[m]), z1 = ALPHA * x1 + gv[bj][1] * (acc[ai][bj][m][1] * rsc[m]);
;                     u32x4 w; w.x = cvt_pk_bf16(z0[0], z0[1]); w.y = cvt_pk_bf16(z0[2], z0[3]); w.z = cvt_pk_bf16(z1[0], z1[1]); w.w = cvt_pk_bf16(z1[2], z1[3]);
;                     *(GAS u32x4*)(O + off + bj * 128) = w; }
;                 if (XF32) asm volatile("" ::: "memory"); } }
	v_pk_mul_f32 v[150:151], v[32:33], v[214:215] op_sel_hi:[1,0]
	v_pk_mul_f32 v[230:231], v[230:231], s[96:97] op_sel_hi:[1,0]
	v_pk_fma_f32 v[230:231], v[200:201], v[150:151], v[230:231]
	v_pk_mul_f32 v[152:153], v[34:35], v[214:215] op_sel_hi:[1,0]
	v_pk_mul_f32 v[232:233], v[232:233], s[96:97] op_sel_hi:[1,0]
	v_pk_fma_f32 v[232:233], v[198:199], v[152:153], v[232:233]
	v_pk_mul_f32 v[150:151], v[28:29], v[214:215] op_sel_hi:[1,0]
	v_pk_mul_f32 v[234:235], v[234:235], s[96:97] op_sel_hi:[1,0]
	v_pk_fma_f32 v[234:235], v[192:193], v[150:151], v[234:235]
	v_pk_mul_f32 v[152:153], v[30:31], v[214:215] op_sel_hi:[1,0]
	v_pk_mul_f32 v[236:237], v[236:237], s[96:97] op_sel_hi:[1,0]
	v_pk_fma_f32 v[236:237], v[190:191], v[152:153], v[236:237]
	v_cvt_pk_bf16_f32 v230, v230, v231
	v_cvt_pk_bf16_f32 v231, v232, v233
	v_cvt_pk_bf16_f32 v232, v234, v235
	v_cvt_pk_bf16_f32 v233, v236, v237
	global_store_dwordx4 v[154:155], v[230:233], off
	v_pk_mul_f32 v[150:151], v[24:25], v[214:215] op_sel_hi:[1,0]
	v_pk_mul_f32 v[238:239], v[238:239], s[96:97] op_sel_hi:[1,0]
	v_pk_fma_f32 v[238:239], v[196:197], v[150:151], v[238:239]
	v_pk_mul_f32 v[152:153], v[26:27], v[214:215] op_sel_hi:[1,0]
	v_pk_mul_f32 v[240:241], v[240:241], s[96:97] op_sel_hi:[1,0]
	v_pk_fma_f32 v[240:241], v[194:195], v[152:153], v[240:241]
	v_pk_mul_f32 v[150:151], v[20:21], v[214:215] op_sel_hi:[1,0]
	v_pk_mul_f32 v[242:243], v[242:243], s[96:97] op_sel_hi:[1,0]
	v_pk_fma_f32 v[242:243], v[188:189], v[150:151], v[242:243]
	v_pk_mul_f32 v[152:153], v[22:23], v[214:215] op_sel_hi:[1,0]
	v_pk_mul_f32 v[244:245], v[244:245], s[96:97] op_sel_hi:[1,0]
	v_pk_fma_f32 v[244:245], v[186:187], v[152:153], v[244:245]
	v_cvt_pk_bf16_f32 v238, v238, v239
	v_cvt_pk_bf16_f32 v239, v240, v241
	v_cvt_pk_bf16_f32 v240, v242, v243
	v_cvt_pk_bf16_f32 v241, v244, v245
	global_store_dwordx4 v[154:155], v[238:241], off offset:256
	v_lshl_add_u64 v[154:155], v[154:155], 0, s[34:35]
	s_waitcnt vmcnt(2)
	v_pk_mul_f32 v[150:151], v[16:17], v[216:217] op_sel_hi:[1,0]
	v_pk_mul_f32 v[246:247], v[246:247], s[96:97] op_sel_hi:[1,0]
	v_pk_fma_f32 v[246:247], v[200:201], v[150:151], v[246:247]
	v_pk_mul_f32 v[152:153], v[18:19], v[216:217] op_sel_hi:[1,0]
	v_pk_mul_f32 v[248:249], v[248:249], s[96:97] op_sel_hi:[1,0]
	v_pk_fma_f32 v[248:249], v[198:199], v[152:153], v[248:249]
	v_pk_mul_f32 v[150:151], v[12:13], v[216:217] op_sel_hi:[1,0]
	v_pk_mul_f32 v[218:219], v[218:219], s[96:97] op_sel_hi:[1,0]
	v_pk_fma_f32 v[218:219], v[192:193], v[150:151], v[218:219]
	v_pk_mul_f32 v[152:153], v[14:15], v[216:217] op_sel_hi:[1,0]
	v_pk_mul_f32 v[220:221], v[220:221], s[96:97] op_sel_hi:[1,0]
	v_pk_fma_f32 v[220:221], v[190:191], v[152:153], v[220:221]
	v_cvt_pk_bf16_f32 v246, v246, v247
	v_cvt_pk_bf16_f32 v247, v248, v249
	v_cvt_pk_bf16_f32 v248, v218, v219
	v_cvt_pk_bf16_f32 v249, v220, v221
	global_store_dwordx4 v[154:155], v[246:249], off
	v_pk_mul_f32 v[150:151], v[8:9], v[216:217] op_sel_hi:[1,0]
	v_pk_mul_f32 v[142:143], v[142:143], s[96:97] op_sel_hi:[1,0]
	v_pk_fma_f32 v[142:143], v[196:197], v[150:151], v[142:143]
	v_pk_mul_f32 v[152:153], v[10:11], v[216:217] op_sel_hi:[1,0]
	v_pk_mul_f32 v[144:145], v[144:145], s[96:97] op_sel_hi:[1,0]
	v_pk_fma_f32 v[144:145], v[194:195], v[152:153], v[144:145]
	v_pk_mul_f32 v[150:151], v[4:5], v[216:217] op_sel_hi:[1,0]
	v_pk_mul_f32 v[146:147], v[146:147], s[96:97] op_sel_hi:[1,0]
	v_pk_fma_f32 v[146:147], v[188:189], v[150:151], v[146:147]
	v_pk_mul_f32 v[152:153], v[6:7], v[216:217] op_sel_hi:[1,0]
	v_pk_mul_f32 v[148:149], v[148:149], s[96:97] op_sel_hi:[1,0]
	v_pk_fma_f32 v[148:149], v[186:187], v[152:153], v[148:149]
	v_cvt_pk_bf16_f32 v142, v142, v143
	v_cvt_pk_bf16_f32 v143, v144, v145
	v_cvt_pk_bf16_f32 v144, v146, v147
	v_cvt_pk_bf16_f32 v145, v148, v149
	global_store_dwordx4 v[154:155], v[142:145], off offset:256
